# P7: half of the workgroups (blockIdx bit 3) process sample items before the prompt item
# speedup vs baseline: 1.0102x; 1.0012x over previous
.LBB0_1048:
	v_readlane_b32 s0, v246, 4
	v_readlane_b32 s1, v246, 5
	s_cmp_lt_i32 s0, 8
	s_cselect_b64 s[0:1], -1, 0
	s_and_b64 s[2:3], s[0:1], s[2:3]
	s_andn2_b64 vcc, exec, s[2:3]
	s_cbranch_vccnz .LBB0_1061
	s_cmpk_gt_i32 s30, 0x2ff
	s_cbranch_scc1 .LBB0_1060
	v_and_b32_e32 v106, 15, v202
	v_mov_b32_e32 v2, 0x8000
	v_readlane_b32 s8, v246, 0
	v_lshrrev_b32_e32 v108, 4, v202
	v_and_or_b32 v122, v202, 7, v2
	v_mul_u32_u24_e32 v2, 0x110, v106
	v_and_b32_e32 v3, 48, v202
	v_add3_u32 v123, s8, v2, v3
	v_lshlrev_b32_e32 v2, 2, v108
	v_bfe_u32 v3, v202, 2, 2
	v_or_b32_e32 v4, v2, v3
	v_lshlrev_b32_e32 v5, 3, v202
	s_add_i32 s2, s8, 0x11000
	v_mul_u32_u24_e32 v4, 0x110, v4
	v_and_b32_e32 v5, 24, v5
	v_lshlrev_b32_e32 v0, 4, v106
	v_add3_u32 v124, s2, v4, v5
	v_add_u32_e32 v4, 0x200, v202
	v_add_u32_e32 v109, s8, v0
	v_lshrrev_b32_e32 v125, 4, v4
	v_add_u32_e32 v4, 0x600, v202
	s_add_u32 s8, s22, 0x195cc000
	v_lshrrev_b32_e32 v127, 4, v4
	v_add_u32_e32 v4, 0xa00, v202
	s_addc_u32 s9, s23, 0
	v_lshrrev_b32_e32 v129, 4, v4
	v_add_u32_e32 v4, 0xe00, v202
	s_add_u32 s10, s22, 0x18fc4000
	v_lshrrev_b32_e32 v131, 4, v4
	v_bfe_u32 v4, v202, 4, 2
	s_addc_u32 s11, s23, 0
	v_lshl_or_b32 v3, v4, 2, v3
	s_add_u32 s12, s22, 0x13aa4000
	v_mul_u32_u24_e32 v3, 0x110, v3
	s_addc_u32 s13, s23, 0
	v_add_u32_e32 v110, s2, v0
	v_and_b32_e32 v0, 8, v202
	v_add3_u32 v133, s2, v3, v5
	s_add_u32 s14, s22, 0x190cc000
	v_lshrrev_b32_e32 v3, 2, v202
	v_lshlrev_b32_e32 v107, 3, v106
	v_cmp_eq_u32_e64 s[6:7], 0, v0
	v_lshlrev_b32_e32 v0, 3, v108
	v_readlane_b32 s36, v246, 38
	s_addc_u32 s15, s23, 0
	v_and_b32_e32 v44, 0x3ffffff0, v3
	v_readlane_b32 s18, v246, 1
	v_mov_b32_e32 v3, 0x13aa4080
	v_lshl_or_b32 v111, v108, 9, v107
	s_waitcnt lgkmcnt(0)
	v_mul_u32_u24_e32 v1, 0x110, v108
	v_or_b32_e32 v113, 64, v108
	v_or_b32_e32 v116, 0x80, v108
	v_or_b32_e32 v119, 0xc0, v108
	v_mov_b32_e32 v41, 0
	v_lshlrev_b32_e32 v40, 5, v106
	v_readlane_b32 s40, v246, 42
	v_readlane_b32 s41, v246, 43
	s_add_u32 s16, s22, 0x192cc000
	v_readlane_b32 s19, v246, 2
	v_lshl_or_b32 v46, v4, 3, v3
	v_mov_b32_e32 v3, 0x195cc080
	v_lshlrev_b32_e32 v50, 1, v0
	v_mbcnt_lo_u32_b32 v0, -1, 0
	v_add_u32_e32 v112, 0x4000, v111
	v_lshl_or_b32 v114, v113, 9, v107
	v_add_u32_e32 v115, 0xc000, v111
	v_lshl_or_b32 v117, v116, 9, v107
	v_add_u32_e32 v118, 0x14000, v111
	v_lshl_or_b32 v120, v119, 9, v107
	v_add_u32_e32 v121, 0x1c000, v111
	v_cmp_gt_u32_e64 s[4:5], 64, v202
	s_mov_b32 s3, 0
	v_mul_u32_u24_e32 v126, 0x110, v125
	v_mul_u32_u24_e32 v128, 0x110, v127
	v_mul_u32_u24_e32 v130, 0x110, v129
	v_mul_u32_u24_e32 v132, 0x110, v131
	v_lshl_add_u64 v[42:43], s[40:41], 0, v[40:41]
	s_addc_u32 s17, s23, 0
	v_mov_b32_e32 v45, v41
	s_lshl_b32 s28, s72, 9
	s_lshl_b32 s29, s18, 9
	v_mov_b32_e32 v47, v41
	v_lshl_or_b32 v48, v4, 4, v3
	v_mov_b32_e32 v49, v41
	v_add_u32_e32 v134, v109, v1
	v_add_u32_e32 v135, v110, v1
	v_mov_b32_e32 v136, 0x358637bd
	s_mov_b32 s30, 0xf149f2ca
	v_lshlrev_b32_e32 v52, 1, v2
	s_mov_b64 s[18:19], 0x200
	s_mov_b64 s[24:25], 0x20000
	v_mbcnt_hi_u32_b32 v137, -1, v0
	v_mov_b32_e32 v138, 0x42000
	s_mov_b32 s31, s72
	v_readlane_b32 s37, v246, 39
	v_readlane_b32 s38, v246, 40
	v_readlane_b32 s39, v246, 41
	v_readlane_b32 s42, v246, 44
	v_readlane_b32 s43, v246, 45
	v_readlane_b32 s44, v246, 46
	v_readlane_b32 s45, v246, 47
	v_readlane_b32 s46, v246, 48
	v_readlane_b32 s47, v246, 49
	v_readlane_b32 s48, v246, 50
	v_readlane_b32 s49, v246, 51
	v_readlane_b32 s50, v246, 52
	v_readlane_b32 s51, v246, 53
	v_readlane_b32 s99, v246, 1
	s_mov_b32 s98, 0
	s_cmpk_lg_i32 s99, 0x100
	s_cbranch_scc1 .Lp7_fwd
	s_bitcmp1_b32 s72, 3
	s_cbranch_scc0 .Lp7_fwd
	s_mov_b32 s98, 1
	s_addk_i32 s31, 0x200
	s_lshl_b32 s28, s31, 9

.LBB0_1051:
	v_readlane_b32 s26, v246, 1
	s_cmp_lg_u32 s98, 0
	s_cbranch_scc1 .Lp7_rev
	s_add_i32 s31, s31, s26
	s_add_i32 s28, s28, s29
	s_cmpk_lt_i32 s31, 0x300
	v_readlane_b32 s27, v246, 2
	s_cbranch_scc0 .LBB0_1060
	s_branch .LBB0_1052
.Lp7_rev:
	s_sub_i32 s31, s31, s26
	s_sub_i32 s28, s28, s29
	s_cmp_gt_i32 s31, -1
	v_readlane_b32 s27, v246, 2
	s_cbranch_scc0 .LBB0_1060

	.amdhsa_kernel _Z10fwd_kernel6Params
		.amdhsa_group_segment_fixed_size 147456
		.amdhsa_private_segment_fixed_size 0
		.amdhsa_kernarg_size 472
		.amdhsa_user_sgpr_count 2
		.amdhsa_user_sgpr_dispatch_ptr 0
		.amdhsa_user_sgpr_queue_ptr 0
		.amdhsa_user_sgpr_kernarg_segment_ptr 1
		.amdhsa_user_sgpr_dispatch_id 0
		.amdhsa_user_sgpr_kernarg_preload_length 0
		.amdhsa_user_sgpr_kernarg_preload_offset 0
		.amdhsa_user_sgpr_private_segment_size 0
		.amdhsa_uses_dynamic_stack 0
		.amdhsa_enable_private_segment 0
		.amdhsa_system_sgpr_workgroup_id_x 1
		.amdhsa_system_sgpr_workgroup_id_y 0
		.amdhsa_system_sgpr_workgroup_id_z 0
		.amdhsa_system_sgpr_workgroup_info 0
		.amdhsa_system_vgpr_workitem_id 2
		.amdhsa_next_free_vgpr 256
		.amdhsa_next_free_sgpr 100
		.amdhsa_accum_offset 256
		.amdhsa_reserve_vcc 1
		.amdhsa_float_round_mode_32 0
		.amdhsa_float_round_mode_16_64 0
		.amdhsa_float_denorm_mode_32 3
		.amdhsa_float_denorm_mode_16_64 3
		.amdhsa_dx10_clamp 1
		.amdhsa_ieee_mode 1
		.amdhsa_fp16_overflow 0
		.amdhsa_tg_split 0
		.amdhsa_exception_fp_ieee_invalid_op 0
		.amdhsa_exception_fp_denorm_src 0
		.amdhsa_exception_fp_ieee_div_zero 0
		.amdhsa_exception_fp_ieee_overflow 0
		.amdhsa_exception_fp_ieee_underflow 0
		.amdhsa_exception_fp_ieee_inexact 0
		.amdhsa_exception_int_div_zero 0
	.end_amdhsa_kernel

amdhsa.kernels:
  - .agpr_count:     0
    .args:
      - .offset:         0
        .size:           216
        .value_kind:     by_value
      - .offset:         216
        .size:           4
        .value_kind:     hidden_block_count_x
      - .offset:         220
        .size:           4
        .value_kind:     hidden_block_count_y
      - .offset:         224
        .size:           4
        .value_kind:     hidden_block_count_z
      - .offset:         228
        .size:           2
        .value_kind:     hidden_group_size_x
      - .offset:         230
        .size:           2
        .value_kind:     hidden_group_size_y
      - .offset:         232
        .size:           2
        .value_kind:     hidden_group_size_z
      - .offset:         234
        .size:           2
        .value_kind:     hidden_remainder_x
      - .offset:         236
        .size:           2
        .value_kind:     hidden_remainder_y
      - .offset:         238
        .size:           2
        .value_kind:     hidden_remainder_z
      - .offset:         256
        .size:           8
        .value_kind:     hidden_global_offset_x
      - .offset:         264
        .size:           8
        .value_kind:     hidden_global_offset_y
      - .offset:         272
        .size:           8
        .value_kind:     hidden_global_offset_z
      - .offset:         280
        .size:           2
        .value_kind:     hidden_grid_dims
      - .offset:         304
        .size:           8
        .value_kind:     hidden_multigrid_sync_arg
    .group_segment_fixed_size: 147456
    .kernarg_segment_align: 8
    .kernarg_segment_size: 472
    .language:       OpenCL C
    .language_version:
      - 2
      - 0
    .max_flat_workgroup_size: 512
    .name:           _Z10fwd_kernel6Params
    .private_segment_fixed_size: 0
    .sgpr_count:     106
    .sgpr_spill_count: 199
    .symbol:         _Z10fwd_kernel6Params.kd
    .uniform_work_group_size: 1
    .uses_dynamic_stack: false
    .vgpr_count:     256
    .vgpr_spill_count: 0
    .wavefront_size: 64
